# attention: L2 prefetch of the unit's three window K/V blocks in the prologue
# baseline (speedup 1.0000x reference)
; __device__ __forceinline__ bool attn_unit(const Ptrs& P, LAS unsigned char* lds, int unit, int tid, int wave, int lane, bool pre, int nxt) {
;     const int n = unit & 31, kh = (unit >> 5) & 3, b = unit >> 7;
;     const int g = wave & 3, q0 = 64 * (wave >> 2), h = kh * 4 + g, r = lane & 31, hh = lane >> 5;
;     unsigned char* ws = P.ws;
;     bf16_t* Qb = (bf16_t*)(ws + WS_Q) + (size_t)(b * SEQ + n * 128 + q0) * DM + h * 64;
;     const bf16_t* Kg = (const bf16_t*)(ws + WS_K) + (size_t)b * SEQ * KVW + kh * 64; const bf16_t* Vg = (const bf16_t*)(ws + WS_VT) + (size_t)(b * 4 + kh) * 64 * SEQ;
;     const bf16_t* Kcg = (const bf16_t*)(ws + WS_KC) + (size_t)b * CTX * KVW + kh * 64; const bf16_t* Vcg = (const bf16_t*)(ws + WS_VCT) + (size_t)(b * 4 + kh) * 64 * CTX;
;     float mq = fabsf(P.qg[lane]), mk = fabsf(P.kg[lane]);
; #pragma unroll
;     for (int o = 1; o < 64; o <<= 1) { mq = fmaxf(mq, __shfl_xor(mq, o)); mk = fmaxf(mk, __shfl_xor(mk, o)); }
;     const float sink2 = P.sink[h] * LOG2E; const float mshift = fmaxf(64.0f * QSCALE * mq * mk, sink2);
;     bf16x8_t qf[2][4];
; #pragma unroll
;     for (int cb = 0; cb < 2; ++cb)
; #pragma unroll
;         for (int ds = 0; ds < 4; ++ds) qf[cb][ds] = __builtin_nontemporal_load((const bf16x8_t*)(Qb + (size_t)(32 * cb + r) * DM + 16 * ds + 8 * hh));
.LBB9_308:
	global_load_dword v0, v[172:173], off
	global_load_dword v2, v[174:175], off
	s_and_b32 s43, s42, 31
	s_ashr_i32 s82, s42, 7
	s_lshl_b32 s47, s43, 7
	s_lshl_b32 s46, s82, 12
	s_add_i32 s70, s47, s33
	s_add_i32 s50, s70, s46
	s_bfe_u32 s44, s42, 0x20005
	s_mov_b32 s46, s50
	s_lshl_b32 s45, s44, 2
	s_ashr_i32 s83, s82, 31
	v_readlane_b32 s48, v251, 40
	s_ashr_i32 s51, s50, 31
	v_writelane_b32 v250, s46, 17
	s_or_b32 s45, s45, s48
	s_lshl_b64 s[48:49], s[82:83], 21
	v_writelane_b32 v250, s47, 18
	s_lshl_b64 s[78:79], s[50:51], 11
	v_readlane_b32 s46, v251, 59
	s_add_u32 s46, s46, s48
	v_readlane_b32 s48, v251, 60
	s_addc_u32 s48, s48, s49
	s_lshl_b32 s49, s44, 7
	s_add_u32 s96, s46, s49
	s_addc_u32 s97, s48, 0
	s_lshl_b32 s46, s82, 2
	s_or_b32 s70, s46, s44
	s_ashr_i32 s71, s70, 31
	s_lshl_b64 s[74:75], s[70:71], 19
	v_readlane_b32 s46, v251, 63
	s_add_u32 s46, s46, s78
	v_readlane_b32 s48, v250, 0
	s_addc_u32 s49, s48, s79
	s_lshl_b32 s48, s45, 7
	s_add_u32 s48, s46, s48
	s_addc_u32 s49, s49, 0
	s_mov_b64 s[88:89], s[72:73]
	s_mov_b64 s[80:81], s[34:35]
	s_mov_b64 s[34:35], s[30:31]
	s_mov_b64 s[30:31], s[28:29]
	s_mov_b64 s[28:29], s[26:27]
	s_mov_b64 s[26:27], s[24:25]
	s_mov_b64 s[24:25], s[22:23]
	s_mov_b64 s[22:23], s[20:21]
	s_mov_b64 s[20:21], s[18:19]
	s_mov_b64 s[18:19], s[16:17]
	s_mov_b64 s[16:17], s[14:15]
	s_mov_b64 s[14:15], s[12:13]
	s_mov_b64 s[12:13], s[10:11]
	s_mov_b64 s[10:11], s[8:9]
	s_mov_b64 s[8:9], s[6:7]
	s_mov_b64 s[6:7], s[4:5]
	s_mov_b64 s[4:5], s[0:1]
	s_mov_b64 s[0:1], s[66:67]
	s_mov_b64 s[40:41], s[64:65]
	s_mov_b64 s[66:67], s[62:63]
	s_mov_b64 s[64:65], s[60:61]
	s_mov_b64 s[72:73], s[56:57]
	s_lshl_b32 s46, s45, 2
	v_lshl_add_u64 v[4:5], s[48:49], 0, v[178:179]
	s_mov_b64 s[78:79], s[54:55]
	v_readlane_b32 s48, v251, 16
	v_mov_b32_e32 v3, s46
	v_readlane_b32 s56, v251, 24
	v_readlane_b32 s57, v251, 25
	v_lshl_add_u64 v[4:5], v[4:5], 0, v[180:181]
	v_readlane_b32 s51, v251, 19
	v_readlane_b32 s46, v250, 1
	v_readlane_b32 s50, v251, 18
	v_readlane_b32 s54, v251, 22
	global_load_dword v3, v3, s[56:57]
	s_nop 0
	global_load_dwordx4 v[114:117], v[4:5], off nt
	global_load_dwordx4 v[118:121], v[4:5], off offset:32 nt
	global_load_dwordx4 v[122:125], v[4:5], off offset:64 nt
	global_load_dwordx4 v[126:129], v[4:5], off offset:96 nt
	v_add_co_u32_e32 v4, vcc, 0x10000, v4
	v_readlane_b32 s55, v251, 23
	s_nop 0
	v_addc_co_u32_e32 v5, vcc, 0, v5, vcc
	global_load_dwordx4 v[130:133], v[4:5], off nt
	global_load_dwordx4 v[134:137], v[4:5], off offset:32 nt
	global_load_dwordx4 v[138:141], v[4:5], off offset:64 nt
	global_load_dwordx4 v[142:145], v[4:5], off offset:96 nt
	s_add_u32 s51, s46, s74
	s_waitcnt vmcnt(9)
	v_and_b32_e32 v4, 0x7fffffff, v0
	v_and_b32_e32 v5, 0x7fffffff, v2
	ds_bpermute_b32 v4, v185, v4
	ds_bpermute_b32 v5, v185, v5
	v_max_f32_e64 v0, |v0|, |v0|
	v_max_f32_e64 v2, |v2|, |v2|
	v_readlane_b32 s46, v250, 2
	s_waitcnt lgkmcnt(1)
	v_max_f32_e32 v4, v4, v4
	s_waitcnt lgkmcnt(0)
	v_max_f32_e32 v5, v5, v5
	v_max_f32_e32 v0, v0, v4
	v_max_f32_e32 v2, v2, v5
	ds_bpermute_b32 v4, v186, v0
	ds_bpermute_b32 v5, v186, v2
	s_mov_b64 s[54:55], s[78:79]
	v_readlane_b32 s50, v251, 32
	s_addc_u32 s46, s46, s75
	s_lshl_b32 s98, s43, 7
	s_addk_i32 s98, 0xff80
	v_add_u32_e32 v252, s98, v208
	v_max_i32_e32 v252, 0, v252
	v_min_i32_e32 v252, 0xfff, v252
	v_lshlrev_b32_e32 v252, 9, v252
	v_mul_u32_u24_e32 v254, 0x2aab, v208
	v_lshrrev_b32_e32 v254, 16, v254
	v_mul_u32_u24_e32 v255, 6, v254
	v_sub_u32_e32 v255, v208, v255
	v_lshlrev_b32_e32 v255, 7, v255
	s_lshl_b32 s98, s98, 1
	v_add_u32_e32 v255, s98, v255
	v_max_i32_e32 v255, 0, v255
	v_min_i32_e32 v255, 0x1f80, v255
	v_lshl_add_u32 v254, v254, 13, v255
	s_mov_b32 s98, s51
	s_mov_b32 s99, s46
	v_cmp_gt_u32_e32 vcc, 0x180, v208
	s_nop 1
	s_and_b64 exec, exec, vcc
	s_cbranch_execz .Lkvpf_done
	global_load_dword v253, v252, s[96:97]
	global_load_dword v253, v254, s[98:99]
.Lkvpf_done:
	s_mov_b64 exec, -1
	s_waitcnt lgkmcnt(1)
	v_max_f32_e32 v4, v4, v4
	s_waitcnt lgkmcnt(0)
	v_max_f32_e32 v5, v5, v5
	v_max_f32_e32 v0, v0, v4
	v_max_f32_e32 v2, v2, v5
	ds_bpermute_b32 v4, v187, v0
	ds_bpermute_b32 v5, v187, v2
	s_and_b64 vcc, exec, s[68:69]
	v_readlane_b32 s49, v251, 17
	v_readlane_b32 s52, v251, 20
	s_waitcnt lgkmcnt(1)
	v_max_f32_e32 v4, v4, v4
	s_waitcnt lgkmcnt(0)
	v_max_f32_e32 v5, v5, v5
	v_max_f32_e32 v0, v0, v4
	v_max_f32_e32 v2, v2, v5
	ds_bpermute_b32 v4, v188, v0
	ds_bpermute_b32 v5, v188, v2
	v_readlane_b32 s53, v251, 21
	v_readlane_b32 s58, v251, 26
	v_readlane_b32 s59, v251, 27
	s_waitcnt lgkmcnt(1)
	v_max_f32_e32 v4, v4, v4
	s_waitcnt lgkmcnt(0)
	v_max_f32_e32 v5, v5, v5
	v_max_f32_e32 v0, v0, v4
	v_max_f32_e32 v2, v2, v5
	ds_bpermute_b32 v4, v189, v0
	ds_bpermute_b32 v5, v189, v2
	v_readlane_b32 s60, v251, 28
	v_readlane_b32 s61, v251, 29
	v_readlane_b32 s62, v251, 30
	s_waitcnt lgkmcnt(1)
	v_max_f32_e32 v4, v4, v4
	s_waitcnt lgkmcnt(0)
	v_max_f32_e32 v5, v5, v5
	v_max_f32_e32 v9, v0, v4
	v_max_f32_e32 v8, v2, v5
	ds_bpermute_b32 v11, v190, v9
	ds_bpermute_b32 v10, v190, v8
	v_readlane_b32 s63, v251, 31
	s_cbranch_vccnz .LBB9_329
	s_cmp_lg_u32 s43, 0
	s_cbranch_scc0 .LBB9_319
	s_andn2_b64 vcc, exec, s[54:55]
	s_cbranch_vccnz .LBB9_318
	s_add_i32 s76, s43, -1
	s_lshl_b64 s[48:49], s[76:77], 16
	s_add_u32 s68, s96, s48
	s_addc_u32 s69, s97, s49
	s_lshl_b32 s48, s76, 8
	s_add_u32 s84, s51, s48
	s_addc_u32 s85, s46, 0
	v_mov_b32_e32 v12, v193
	v_mov_b32_e32 v2, v192
	s_mov_b32 s76, s50
	s_branch .LBB9_314
